# baseline (speedup 1.0000x reference)
; DEVINL u16 f2bf(float f) { uint32_t u = __float_as_uint(f); u += 0x7FFFu + ((u >> 16) & 1u); return (u16)(u >> 16); }
; DEVINL float bfs2f(short h) { return __uint_as_float(((uint32_t)(u16)h) << 16); }
; DEVINL void phase_scan(const Params& p, int layer, int wv) {
;     ...
;     for (int c = 0; c < 32; ++c) {
;       u16* sp = stg + ((size_t)((b * 32 + c) * 16 + hd)) * 8192 + e;
;       bf16x8 r = *(const bf16x8*)sp;
;       float cd = __expf(acumg[(size_t)(b * SEQ + c * 128 + 127) * 16 + hd]);
;       bf16x8 o;
; #pragma unroll
;       for (int k = 0; k < 8; ++k) { o[k] = (short)f2bf(carry[k]); carry[k] = carry[k] * cd + bfs2f(r[k]); }
;       *(bf16x8*)sp = o;
;     }
.LBB0_757:
	v_lshl_add_u64 v[38:39], s[94:95], 0, v[6:7]
	s_mov_b32 s99, 0
	v_lshl_add_u64 v[148:149], s[94:95], 0, v[36:37]
	global_load_dwordx4 v[68:71], v[148:149], off
	s_mov_b32 s98, 0x1dd05000
	v_lshl_add_u64 v[150:151], v[38:39], 0, s[98:99]
	global_load_dword v132, v[150:151], off offset:1728
	v_lshl_add_u64 v[148:149], s[94:95], 0, v[34:35]
	global_load_dwordx4 v[72:75], v[148:149], off
	s_mov_b32 s98, 0x1dd07000
	v_lshl_add_u64 v[150:151], v[38:39], 0, s[98:99]
	global_load_dword v133, v[150:151], off offset:1728
	v_lshl_add_u64 v[148:149], s[94:95], 0, v[32:33]
	global_load_dwordx4 v[76:79], v[148:149], off
	s_mov_b32 s98, 0x1dd09000
	v_lshl_add_u64 v[150:151], v[38:39], 0, s[98:99]
	global_load_dword v134, v[150:151], off offset:1728
	v_lshl_add_u64 v[148:149], s[94:95], 0, v[30:31]
	global_load_dwordx4 v[80:83], v[148:149], off
	s_mov_b32 s98, 0x1dd0b000
	v_lshl_add_u64 v[150:151], v[38:39], 0, s[98:99]
	global_load_dword v135, v[150:151], off offset:1728
	v_lshl_add_u64 v[148:149], s[94:95], 0, v[28:29]
	global_load_dwordx4 v[84:87], v[148:149], off
	s_mov_b32 s98, 0x1dd0d000
	v_lshl_add_u64 v[150:151], v[38:39], 0, s[98:99]
	global_load_dword v136, v[150:151], off offset:1728
	v_lshl_add_u64 v[148:149], s[94:95], 0, v[26:27]
	global_load_dwordx4 v[88:91], v[148:149], off
	s_mov_b32 s98, 0x1dd0f000
	v_lshl_add_u64 v[150:151], v[38:39], 0, s[98:99]
	global_load_dword v137, v[150:151], off offset:1728
	v_lshl_add_u64 v[148:149], s[94:95], 0, v[24:25]
	global_load_dwordx4 v[92:95], v[148:149], off
	s_mov_b32 s98, 0x1dd11000
	v_lshl_add_u64 v[150:151], v[38:39], 0, s[98:99]
	global_load_dword v138, v[150:151], off offset:1728
	v_lshl_add_u64 v[148:149], s[94:95], 0, v[22:23]
	global_load_dwordx4 v[96:99], v[148:149], off
	s_mov_b32 s98, 0x1dd13000
	v_lshl_add_u64 v[150:151], v[38:39], 0, s[98:99]
	global_load_dword v139, v[150:151], off offset:1728
	v_lshl_add_u64 v[148:149], s[94:95], 0, v[20:21]
	global_load_dwordx4 v[100:103], v[148:149], off
	s_mov_b32 s98, 0x1dd15000
	v_lshl_add_u64 v[150:151], v[38:39], 0, s[98:99]
	global_load_dword v140, v[150:151], off offset:1728
	v_lshl_add_u64 v[148:149], s[94:95], 0, v[18:19]
	global_load_dwordx4 v[104:107], v[148:149], off
	s_mov_b32 s98, 0x1dd17000
	v_lshl_add_u64 v[150:151], v[38:39], 0, s[98:99]
	global_load_dword v141, v[150:151], off offset:1728
	v_lshl_add_u64 v[148:149], s[94:95], 0, v[16:17]
	global_load_dwordx4 v[108:111], v[148:149], off
	s_mov_b32 s98, 0x1dd19000
	v_lshl_add_u64 v[150:151], v[38:39], 0, s[98:99]
	global_load_dword v142, v[150:151], off offset:1728
	v_lshl_add_u64 v[148:149], s[94:95], 0, v[14:15]
	global_load_dwordx4 v[112:115], v[148:149], off
	s_mov_b32 s98, 0x1dd1b000
	v_lshl_add_u64 v[150:151], v[38:39], 0, s[98:99]
	global_load_dword v143, v[150:151], off offset:1728
	v_lshl_add_u64 v[148:149], s[94:95], 0, v[12:13]
	global_load_dwordx4 v[116:119], v[148:149], off
	s_mov_b32 s98, 0x1dd1d000
	v_lshl_add_u64 v[150:151], v[38:39], 0, s[98:99]
	global_load_dword v144, v[150:151], off offset:1728
	v_lshl_add_u64 v[148:149], s[94:95], 0, v[10:11]
	global_load_dwordx4 v[120:123], v[148:149], off
	s_mov_b32 s98, 0x1dd1f000
	v_lshl_add_u64 v[150:151], v[38:39], 0, s[98:99]
	global_load_dword v145, v[150:151], off offset:1728
	v_lshl_add_u64 v[148:149], s[94:95], 0, v[8:9]
	global_load_dwordx4 v[124:127], v[148:149], off
	s_mov_b32 s98, 0x1dd21000
	v_lshl_add_u64 v[150:151], v[38:39], 0, s[98:99]
	global_load_dword v146, v[150:151], off offset:1728
	v_lshl_add_u64 v[148:149], s[94:95], 0, v[4:5]
	global_load_dwordx4 v[128:131], v[148:149], off
	s_mov_b32 s98, 0x1dd23000
	v_lshl_add_u64 v[150:151], v[38:39], 0, s[98:99]
	global_load_dword v147, v[150:151], off offset:1728
	s_mov_b32 s26, 0x1dd05000
	v_add_co_u32_e32 v46, vcc, s26, v38
	v_lshl_add_u64 v[54:55], s[94:95], 0, v[36:37]
	s_nop 0
	v_addc_co_u32_e32 v47, vcc, 0, v39, vcc
	v_bfe_u32 v48, v41, 16, 1
	v_bfe_u32 v47, v50, 16, 1
	v_bfe_u32 v49, v40, 16, 1
	v_bfe_u32 v57, v3, 16, 1
	v_bfe_u32 v58, v2, 16, 1
	v_bfe_u32 v59, v1, 16, 1
	v_bfe_u32 v60, v0, 16, 1
	v_add3_u32 v60, v0, v60, s12
	v_add3_u32 v59, v1, v59, s12
	v_add3_u32 v58, v2, v58, s12
	v_add3_u32 v57, v3, v57, s12
	v_add3_u32 v61, v40, v49, s12
	v_add3_u32 v48, v41, v48, s12
	v_add3_u32 v47, v50, v47, s12
	v_perm_b32 v48, v48, v61, s13
	s_mov_b32 s26, 0x1dd07000
	s_add_i32 s25, s25, -16
	v_lshl_add_u64 v[6:7], v[6:7], 0, s[8:9]
	v_lshl_add_u64 v[36:37], v[36:37], 0, s[6:7]
	s_cmp_eq_u32 s25, 0
	s_waitcnt vmcnt(31)
	v_and_b32_e32 v61, 0xffff0000, v69
	v_and_b32_e32 v63, 0xffff0000, v71
	s_waitcnt vmcnt(30)
	v_mul_f32_e32 v46, 0x3fb8aa3b, v132
	v_exp_f32_e32 v56, v46
	v_bfe_u32 v46, v51, 16, 1
	v_add3_u32 v46, v51, v46, s12
	v_perm_b32 v49, v46, v47, s13
	v_perm_b32 v47, v57, v58, s13
	v_perm_b32 v46, v59, v60, s13
	v_and_b32_e32 v59, 0xffff0000, v68
	v_lshlrev_b32_e32 v58, 16, v68
	v_lshlrev_b32_e32 v60, 16, v69
	v_and_b32_e32 v43, 0xffff0000, v70
	v_lshlrev_b32_e32 v42, 16, v70
	v_lshlrev_b32_e32 v62, 16, v71
	v_pk_fma_f32 v[44:45], v[50:51], v[56:57], v[62:63] op_sel_hi:[1,0,1]
	v_pk_fma_f32 v[50:51], v[40:41], v[56:57], v[42:43] op_sel_hi:[1,0,1]
	v_add_co_u32_e32 v40, vcc, s26, v38
	global_store_dwordx4 v[54:55], v[46:49], off
	s_nop 0
	v_addc_co_u32_e32 v41, vcc, 0, v39, vcc
	v_lshl_add_u64 v[46:47], s[94:95], 0, v[34:35]
	v_pk_fma_f32 v[60:61], v[2:3], v[56:57], v[60:61] op_sel_hi:[1,0,1]
	v_pk_fma_f32 v[56:57], v[0:1], v[56:57], v[58:59] op_sel_hi:[1,0,1]
	v_bfe_u32 v42, v51, 16, 1
	v_bfe_u32 v41, v44, 16, 1
	v_bfe_u32 v43, v50, 16, 1
	v_bfe_u32 v49, v61, 16, 1
	v_bfe_u32 v54, v60, 16, 1
	v_bfe_u32 v55, v57, 16, 1
	v_bfe_u32 v58, v56, 16, 1
	v_add3_u32 v58, v56, v58, s12
	v_add3_u32 v55, v57, v55, s12
	v_add3_u32 v54, v60, v54, s12
	v_add3_u32 v49, v61, v49, s12
	v_add3_u32 v59, v50, v43, s12
	v_add3_u32 v42, v51, v42, s12
	v_add3_u32 v41, v44, v41, s12
	v_perm_b32 v42, v42, v59, s13
	s_mov_b32 s26, 0x1dd09000
	v_lshl_add_u64 v[34:35], v[34:35], 0, s[6:7]
	s_waitcnt vmcnt(30)
; DEVINL u16 f2bf(float f) { uint32_t u = __float_as_uint(f); u += 0x7FFFu + ((u >> 16) & 1u); return (u16)(u >> 16); }
; DEVINL float bfs2f(short h) { return __uint_as_float(((uint32_t)(u16)h) << 16); }
; DEVINL void phase_scan(const Params& p, int layer, int wv) {
;     ...
;     for (int c = 0; c < 32; ++c) {
;       u16* sp = stg + ((size_t)((b * 32 + c) * 16 + hd)) * 8192 + e;
;       bf16x8 r = *(const bf16x8*)sp;
;       float cd = __expf(acumg[(size_t)(b * SEQ + c * 128 + 127) * 16 + hd]);
;       bf16x8 o;
; #pragma unroll
;       for (int k = 0; k < 8; ++k) { o[k] = (short)f2bf(carry[k]); carry[k] = carry[k] * cd + bfs2f(r[k]); }
;       *(bf16x8*)sp = o;
;     }
	v_and_b32_e32 v59, 0xffff0000, v73
	v_and_b32_e32 v63, 0xffff0000, v75
	s_waitcnt vmcnt(29)
	v_mul_f32_e32 v40, 0x3fb8aa3b, v133
	v_exp_f32_e32 v48, v40
	v_bfe_u32 v40, v45, 16, 1
	v_add3_u32 v40, v45, v40, s12
	v_perm_b32 v43, v40, v41, s13
	v_perm_b32 v41, v49, v54, s13
	v_perm_b32 v40, v55, v58, s13
	global_store_dwordx4 v[46:47], v[40:43], off
	v_and_b32_e32 v55, 0xffff0000, v72
	v_lshlrev_b32_e32 v54, 16, v72
	v_add_co_u32_e32 v40, vcc, s26, v38
	v_lshlrev_b32_e32 v58, 16, v73
	v_and_b32_e32 v1, 0xffff0000, v74
	v_lshlrev_b32_e32 v0, 16, v74
	v_lshl_add_u64 v[46:47], s[94:95], 0, v[32:33]
	v_addc_co_u32_e32 v41, vcc, 0, v39, vcc
	v_lshlrev_b32_e32 v62, 16, v75
	v_pk_fma_f32 v[50:51], v[50:51], v[48:49], v[0:1] op_sel_hi:[1,0,1]
	v_pk_fma_f32 v[44:45], v[44:45], v[48:49], v[62:63] op_sel_hi:[1,0,1]
	v_pk_fma_f32 v[58:59], v[60:61], v[48:49], v[58:59] op_sel_hi:[1,0,1]
	v_pk_fma_f32 v[48:49], v[56:57], v[48:49], v[54:55] op_sel_hi:[1,0,1]
	v_bfe_u32 v41, v44, 16, 1
	v_bfe_u32 v42, v51, 16, 1
	v_bfe_u32 v43, v50, 16, 1
	v_bfe_u32 v55, v59, 16, 1
	v_bfe_u32 v56, v58, 16, 1
	v_bfe_u32 v57, v49, 16, 1
	v_bfe_u32 v60, v48, 16, 1
	v_add3_u32 v60, v48, v60, s12
	v_add3_u32 v57, v49, v57, s12
	v_add3_u32 v56, v58, v56, s12
	v_add3_u32 v55, v59, v55, s12
	v_add3_u32 v61, v50, v43, s12
	v_add3_u32 v42, v51, v42, s12
	v_add3_u32 v41, v44, v41, s12
	v_perm_b32 v42, v42, v61, s13
	s_mov_b32 s26, 0x1dd0b000
	v_lshl_add_u64 v[32:33], v[32:33], 0, s[6:7]
	s_waitcnt vmcnt(29)
	v_and_b32_e32 v61, 0xffff0000, v77
	v_and_b32_e32 v63, 0xffff0000, v79
	s_waitcnt vmcnt(28)
	v_mul_f32_e32 v40, 0x3fb8aa3b, v134
	v_exp_f32_e32 v54, v40
	v_bfe_u32 v40, v45, 16, 1
	v_add3_u32 v40, v45, v40, s12
	v_perm_b32 v43, v40, v41, s13
	v_perm_b32 v41, v55, v56, s13
	v_perm_b32 v40, v57, v60, s13
	global_store_dwordx4 v[46:47], v[40:43], off
	v_and_b32_e32 v57, 0xffff0000, v76
	v_lshlrev_b32_e32 v56, 16, v76
	v_add_co_u32_e32 v40, vcc, s26, v38
	v_lshlrev_b32_e32 v60, 16, v77
	v_and_b32_e32 v1, 0xffff0000, v78
	v_lshlrev_b32_e32 v0, 16, v78
	v_lshl_add_u64 v[46:47], s[94:95], 0, v[30:31]
	v_addc_co_u32_e32 v41, vcc, 0, v39, vcc
	v_lshlrev_b32_e32 v62, 16, v79
	v_pk_fma_f32 v[50:51], v[50:51], v[54:55], v[0:1] op_sel_hi:[1,0,1]
	v_pk_fma_f32 v[44:45], v[44:45], v[54:55], v[62:63] op_sel_hi:[1,0,1]
	v_pk_fma_f32 v[58:59], v[58:59], v[54:55], v[60:61] op_sel_hi:[1,0,1]
	v_pk_fma_f32 v[48:49], v[48:49], v[54:55], v[56:57] op_sel_hi:[1,0,1]
	v_bfe_u32 v41, v44, 16, 1
	v_bfe_u32 v42, v51, 16, 1
	v_bfe_u32 v43, v50, 16, 1
	v_bfe_u32 v55, v59, 16, 1
	v_bfe_u32 v56, v58, 16, 1
	v_bfe_u32 v57, v49, 16, 1
	v_bfe_u32 v60, v48, 16, 1
	v_add3_u32 v60, v48, v60, s12
	v_add3_u32 v57, v49, v57, s12
	v_add3_u32 v56, v58, v56, s12
	v_add3_u32 v55, v59, v55, s12
	v_add3_u32 v61, v50, v43, s12
	v_add3_u32 v42, v51, v42, s12
	v_add3_u32 v41, v44, v41, s12
	v_perm_b32 v42, v42, v61, s13
	s_mov_b32 s26, 0x1dd0d000
	v_lshl_add_u64 v[30:31], v[30:31], 0, s[6:7]
	s_waitcnt vmcnt(28)
	v_and_b32_e32 v61, 0xffff0000, v81
	v_and_b32_e32 v63, 0xffff0000, v83
	s_waitcnt vmcnt(27)
	v_mul_f32_e32 v40, 0x3fb8aa3b, v135
	v_exp_f32_e32 v54, v40
	v_bfe_u32 v40, v45, 16, 1
	v_add3_u32 v40, v45, v40, s12
	v_perm_b32 v43, v40, v41, s13
	v_perm_b32 v41, v55, v56, s13
	v_perm_b32 v40, v57, v60, s13
	global_store_dwordx4 v[46:47], v[40:43], off
	v_and_b32_e32 v57, 0xffff0000, v80
	v_lshlrev_b32_e32 v56, 16, v80
	v_add_co_u32_e32 v40, vcc, s26, v38
	v_lshlrev_b32_e32 v60, 16, v81
	v_and_b32_e32 v1, 0xffff0000, v82
	v_lshlrev_b32_e32 v0, 16, v82
	v_lshl_add_u64 v[46:47], s[94:95], 0, v[28:29]
	v_addc_co_u32_e32 v41, vcc, 0, v39, vcc
	v_lshlrev_b32_e32 v62, 16, v83
	v_pk_fma_f32 v[50:51], v[50:51], v[54:55], v[0:1] op_sel_hi:[1,0,1]
	v_pk_fma_f32 v[44:45], v[44:45], v[54:55], v[62:63] op_sel_hi:[1,0,1]
	v_pk_fma_f32 v[58:59], v[58:59], v[54:55], v[60:61] op_sel_hi:[1,0,1]
	v_pk_fma_f32 v[48:49], v[48:49], v[54:55], v[56:57] op_sel_hi:[1,0,1]
	v_bfe_u32 v41, v44, 16, 1
	v_bfe_u32 v42, v51, 16, 1
	v_bfe_u32 v43, v50, 16, 1
	v_bfe_u32 v55, v59, 16, 1
	v_bfe_u32 v56, v58, 16, 1
	v_bfe_u32 v57, v49, 16, 1
	v_bfe_u32 v60, v48, 16, 1
	v_add3_u32 v60, v48, v60, s12
	v_add3_u32 v57, v49, v57, s12
	v_add3_u32 v56, v58, v56, s12
	v_add3_u32 v55, v59, v55, s12
	v_add3_u32 v61, v50, v43, s12
	v_add3_u32 v42, v51, v42, s12
	v_add3_u32 v41, v44, v41, s12
	v_perm_b32 v42, v42, v61, s13
	s_mov_b32 s26, 0x1dd0f000
	v_lshl_add_u64 v[28:29], v[28:29], 0, s[6:7]
	s_waitcnt vmcnt(27)
	v_and_b32_e32 v61, 0xffff0000, v85
	v_and_b32_e32 v63, 0xffff0000, v87
	s_waitcnt vmcnt(26)
	v_mul_f32_e32 v40, 0x3fb8aa3b, v136
	v_exp_f32_e32 v54, v40
	v_bfe_u32 v40, v45, 16, 1
	v_add3_u32 v40, v45, v40, s12
	v_perm_b32 v43, v40, v41, s13
	v_perm_b32 v41, v55, v56, s13
	v_perm_b32 v40, v57, v60, s13
	global_store_dwordx4 v[46:47], v[40:43], off
	v_and_b32_e32 v57, 0xffff0000, v84
	v_lshlrev_b32_e32 v56, 16, v84
	v_add_co_u32_e32 v40, vcc, s26, v38
	v_lshlrev_b32_e32 v60, 16, v85
	v_and_b32_e32 v1, 0xffff0000, v86
	v_lshlrev_b32_e32 v0, 16, v86
	v_lshl_add_u64 v[46:47], s[94:95], 0, v[26:27]
	v_addc_co_u32_e32 v41, vcc, 0, v39, vcc
	v_lshlrev_b32_e32 v62, 16, v87
	v_pk_fma_f32 v[50:51], v[50:51], v[54:55], v[0:1] op_sel_hi:[1,0,1]
	v_pk_fma_f32 v[44:45], v[44:45], v[54:55], v[62:63] op_sel_hi:[1,0,1]
	v_pk_fma_f32 v[58:59], v[58:59], v[54:55], v[60:61] op_sel_hi:[1,0,1]
	v_pk_fma_f32 v[48:49], v[48:49], v[54:55], v[56:57] op_sel_hi:[1,0,1]
	v_bfe_u32 v41, v44, 16, 1
	v_bfe_u32 v42, v51, 16, 1
	v_bfe_u32 v43, v50, 16, 1
	v_bfe_u32 v55, v59, 16, 1
	v_bfe_u32 v56, v58, 16, 1
	v_bfe_u32 v57, v49, 16, 1
	v_bfe_u32 v60, v48, 16, 1
	v_add3_u32 v60, v48, v60, s12
	v_add3_u32 v57, v49, v57, s12
	v_add3_u32 v56, v58, v56, s12
	v_add3_u32 v55, v59, v55, s12
	v_add3_u32 v61, v50, v43, s12
	v_add3_u32 v42, v51, v42, s12
	v_add3_u32 v41, v44, v41, s12
	v_perm_b32 v42, v42, v61, s13
	v_lshl_add_u64 v[26:27], v[26:27], 0, s[6:7]
	s_waitcnt vmcnt(26)
; DEVINL u16 f2bf(float f) { uint32_t u = __float_as_uint(f); u += 0x7FFFu + ((u >> 16) & 1u); return (u16)(u >> 16); }
; DEVINL float bfs2f(short h) { return __uint_as_float(((uint32_t)(u16)h) << 16); }
; DEVINL void phase_scan(const Params& p, int layer, int wv) {
;     ...
;     for (int c = 0; c < 32; ++c) {
;       u16* sp = stg + ((size_t)((b * 32 + c) * 16 + hd)) * 8192 + e;
;       bf16x8 r = *(const bf16x8*)sp;
;       float cd = __expf(acumg[(size_t)(b * SEQ + c * 128 + 127) * 16 + hd]);
;       bf16x8 o;
; #pragma unroll
;       for (int k = 0; k < 8; ++k) { o[k] = (short)f2bf(carry[k]); carry[k] = carry[k] * cd + bfs2f(r[k]); }
;       *(bf16x8*)sp = o;
;     }
	v_and_b32_e32 v61, 0xffff0000, v89
	v_and_b32_e32 v63, 0xffff0000, v91
	s_waitcnt vmcnt(25)
	v_mul_f32_e32 v40, 0x3fb8aa3b, v137
	v_exp_f32_e32 v54, v40
	v_bfe_u32 v40, v45, 16, 1
	v_add3_u32 v40, v45, v40, s12
	v_perm_b32 v43, v40, v41, s13
	v_perm_b32 v41, v55, v56, s13
	v_perm_b32 v40, v57, v60, s13
	global_store_dwordx4 v[46:47], v[40:43], off
	v_and_b32_e32 v57, 0xffff0000, v88
	v_lshlrev_b32_e32 v56, 16, v88
	v_add_co_u32_e32 v40, vcc, s14, v38
	v_lshlrev_b32_e32 v60, 16, v89
	v_and_b32_e32 v1, 0xffff0000, v90
	v_lshlrev_b32_e32 v0, 16, v90
	v_lshl_add_u64 v[46:47], s[94:95], 0, v[24:25]
	v_addc_co_u32_e32 v41, vcc, 0, v39, vcc
	v_lshlrev_b32_e32 v62, 16, v91
	v_pk_fma_f32 v[50:51], v[50:51], v[54:55], v[0:1] op_sel_hi:[1,0,1]
	v_pk_fma_f32 v[44:45], v[44:45], v[54:55], v[62:63] op_sel_hi:[1,0,1]
	v_pk_fma_f32 v[58:59], v[58:59], v[54:55], v[60:61] op_sel_hi:[1,0,1]
	v_pk_fma_f32 v[48:49], v[48:49], v[54:55], v[56:57] op_sel_hi:[1,0,1]
	v_bfe_u32 v41, v44, 16, 1
	v_bfe_u32 v42, v51, 16, 1
	v_bfe_u32 v43, v50, 16, 1
	v_bfe_u32 v55, v59, 16, 1
	v_bfe_u32 v56, v58, 16, 1
	v_bfe_u32 v57, v49, 16, 1
	v_bfe_u32 v60, v48, 16, 1
	v_add3_u32 v60, v48, v60, s12
	v_add3_u32 v57, v49, v57, s12
	v_add3_u32 v56, v58, v56, s12
	v_add3_u32 v55, v59, v55, s12
	v_add3_u32 v61, v50, v43, s12
	v_add3_u32 v42, v51, v42, s12
	v_add3_u32 v41, v44, v41, s12
	v_perm_b32 v42, v42, v61, s13
	v_lshl_add_u64 v[24:25], v[24:25], 0, s[6:7]
	s_waitcnt vmcnt(25)
	v_and_b32_e32 v61, 0xffff0000, v93
	v_and_b32_e32 v63, 0xffff0000, v95
	s_waitcnt vmcnt(24)
	v_mul_f32_e32 v40, 0x3fb8aa3b, v138
	v_exp_f32_e32 v54, v40
	v_bfe_u32 v40, v45, 16, 1
	v_add3_u32 v40, v45, v40, s12
	v_perm_b32 v43, v40, v41, s13
	v_perm_b32 v41, v55, v56, s13
	v_perm_b32 v40, v57, v60, s13
	global_store_dwordx4 v[46:47], v[40:43], off
	v_and_b32_e32 v57, 0xffff0000, v92
	v_lshlrev_b32_e32 v56, 16, v92
	v_add_co_u32_e32 v40, vcc, s15, v38
	v_lshlrev_b32_e32 v60, 16, v93
	v_and_b32_e32 v1, 0xffff0000, v94
	v_lshlrev_b32_e32 v0, 16, v94
	v_lshl_add_u64 v[46:47], s[94:95], 0, v[22:23]
	v_addc_co_u32_e32 v41, vcc, 0, v39, vcc
	v_lshlrev_b32_e32 v62, 16, v95
	v_pk_fma_f32 v[50:51], v[50:51], v[54:55], v[0:1] op_sel_hi:[1,0,1]
	v_pk_fma_f32 v[44:45], v[44:45], v[54:55], v[62:63] op_sel_hi:[1,0,1]
	v_pk_fma_f32 v[58:59], v[58:59], v[54:55], v[60:61] op_sel_hi:[1,0,1]
	v_pk_fma_f32 v[48:49], v[48:49], v[54:55], v[56:57] op_sel_hi:[1,0,1]
	v_bfe_u32 v41, v44, 16, 1
	v_bfe_u32 v42, v51, 16, 1
	v_bfe_u32 v43, v50, 16, 1
	v_bfe_u32 v55, v59, 16, 1
	v_bfe_u32 v56, v58, 16, 1
	v_bfe_u32 v57, v49, 16, 1
	v_bfe_u32 v60, v48, 16, 1
	v_add3_u32 v60, v48, v60, s12
	v_add3_u32 v57, v49, v57, s12
	v_add3_u32 v56, v58, v56, s12
	v_add3_u32 v55, v59, v55, s12
	v_add3_u32 v61, v50, v43, s12
	v_add3_u32 v42, v51, v42, s12
	v_add3_u32 v41, v44, v41, s12
	v_perm_b32 v42, v42, v61, s13
	v_lshl_add_u64 v[22:23], v[22:23], 0, s[6:7]
	s_waitcnt vmcnt(24)
	v_and_b32_e32 v61, 0xffff0000, v97
	v_and_b32_e32 v63, 0xffff0000, v99
	s_waitcnt vmcnt(23)
	v_mul_f32_e32 v40, 0x3fb8aa3b, v139
	v_exp_f32_e32 v54, v40
	v_bfe_u32 v40, v45, 16, 1
	v_add3_u32 v40, v45, v40, s12
	v_perm_b32 v43, v40, v41, s13
	v_perm_b32 v41, v55, v56, s13
	v_perm_b32 v40, v57, v60, s13
	global_store_dwordx4 v[46:47], v[40:43], off
	v_and_b32_e32 v57, 0xffff0000, v96
	v_lshlrev_b32_e32 v56, 16, v96
	v_add_co_u32_e32 v40, vcc, s16, v38
	v_lshlrev_b32_e32 v60, 16, v97
	v_and_b32_e32 v1, 0xffff0000, v98
	v_lshlrev_b32_e32 v0, 16, v98
	v_lshl_add_u64 v[46:47], s[94:95], 0, v[20:21]
	v_addc_co_u32_e32 v41, vcc, 0, v39, vcc
	v_lshlrev_b32_e32 v62, 16, v99
	v_pk_fma_f32 v[50:51], v[50:51], v[54:55], v[0:1] op_sel_hi:[1,0,1]
	v_pk_fma_f32 v[44:45], v[44:45], v[54:55], v[62:63] op_sel_hi:[1,0,1]
	v_pk_fma_f32 v[58:59], v[58:59], v[54:55], v[60:61] op_sel_hi:[1,0,1]
	v_pk_fma_f32 v[48:49], v[48:49], v[54:55], v[56:57] op_sel_hi:[1,0,1]
	v_bfe_u32 v41, v44, 16, 1
	v_bfe_u32 v42, v51, 16, 1
	v_bfe_u32 v43, v50, 16, 1
	v_bfe_u32 v55, v59, 16, 1
	v_bfe_u32 v56, v58, 16, 1
	v_bfe_u32 v57, v49, 16, 1
	v_bfe_u32 v60, v48, 16, 1
	v_add3_u32 v60, v48, v60, s12
	v_add3_u32 v57, v49, v57, s12
	v_add3_u32 v56, v58, v56, s12
	v_add3_u32 v55, v59, v55, s12
	v_add3_u32 v61, v50, v43, s12
	v_add3_u32 v42, v51, v42, s12
	v_add3_u32 v41, v44, v41, s12
	v_perm_b32 v42, v42, v61, s13
	v_lshl_add_u64 v[20:21], v[20:21], 0, s[6:7]
	s_waitcnt vmcnt(23)
	v_and_b32_e32 v61, 0xffff0000, v101
	v_and_b32_e32 v63, 0xffff0000, v103
	s_waitcnt vmcnt(22)
	v_mul_f32_e32 v40, 0x3fb8aa3b, v140
	v_exp_f32_e32 v54, v40
	v_bfe_u32 v40, v45, 16, 1
	v_add3_u32 v40, v45, v40, s12
	v_perm_b32 v43, v40, v41, s13
	v_perm_b32 v41, v55, v56, s13
	v_perm_b32 v40, v57, v60, s13
	global_store_dwordx4 v[46:47], v[40:43], off
	v_and_b32_e32 v57, 0xffff0000, v100
	v_lshlrev_b32_e32 v56, 16, v100
	v_add_co_u32_e32 v40, vcc, s17, v38
	v_lshlrev_b32_e32 v60, 16, v101
	v_and_b32_e32 v1, 0xffff0000, v102
	v_lshlrev_b32_e32 v0, 16, v102
	v_lshl_add_u64 v[46:47], s[94:95], 0, v[18:19]
	v_addc_co_u32_e32 v41, vcc, 0, v39, vcc
	v_lshlrev_b32_e32 v62, 16, v103
	v_pk_fma_f32 v[50:51], v[50:51], v[54:55], v[0:1] op_sel_hi:[1,0,1]
	v_pk_fma_f32 v[44:45], v[44:45], v[54:55], v[62:63] op_sel_hi:[1,0,1]
	v_pk_fma_f32 v[58:59], v[58:59], v[54:55], v[60:61] op_sel_hi:[1,0,1]
	v_pk_fma_f32 v[48:49], v[48:49], v[54:55], v[56:57] op_sel_hi:[1,0,1]
	v_bfe_u32 v41, v44, 16, 1
	v_bfe_u32 v42, v51, 16, 1
	v_bfe_u32 v43, v50, 16, 1
	v_bfe_u32 v55, v59, 16, 1
	v_bfe_u32 v56, v58, 16, 1
	v_bfe_u32 v57, v49, 16, 1
	v_bfe_u32 v60, v48, 16, 1
	v_add3_u32 v60, v48, v60, s12
	v_add3_u32 v57, v49, v57, s12
	v_add3_u32 v56, v58, v56, s12
	v_add3_u32 v55, v59, v55, s12
	v_add3_u32 v61, v50, v43, s12
	v_add3_u32 v42, v51, v42, s12
	v_add3_u32 v41, v44, v41, s12
	v_perm_b32 v42, v42, v61, s13
	v_lshl_add_u64 v[18:19], v[18:19], 0, s[6:7]
	s_waitcnt vmcnt(22)
; DEVINL u16 f2bf(float f) { uint32_t u = __float_as_uint(f); u += 0x7FFFu + ((u >> 16) & 1u); return (u16)(u >> 16); }
; DEVINL float bfs2f(short h) { return __uint_as_float(((uint32_t)(u16)h) << 16); }
; DEVINL void phase_scan(const Params& p, int layer, int wv) {
;     ...
;     for (int c = 0; c < 32; ++c) {
;       u16* sp = stg + ((size_t)((b * 32 + c) * 16 + hd)) * 8192 + e;
;       bf16x8 r = *(const bf16x8*)sp;
;       float cd = __expf(acumg[(size_t)(b * SEQ + c * 128 + 127) * 16 + hd]);
;       bf16x8 o;
; #pragma unroll
;       for (int k = 0; k < 8; ++k) { o[k] = (short)f2bf(carry[k]); carry[k] = carry[k] * cd + bfs2f(r[k]); }
;       *(bf16x8*)sp = o;
;     }
	v_and_b32_e32 v61, 0xffff0000, v105
	v_and_b32_e32 v63, 0xffff0000, v107
	s_waitcnt vmcnt(21)
	v_mul_f32_e32 v40, 0x3fb8aa3b, v141
	v_exp_f32_e32 v54, v40
	v_bfe_u32 v40, v45, 16, 1
	v_add3_u32 v40, v45, v40, s12
	v_perm_b32 v43, v40, v41, s13
	v_perm_b32 v41, v55, v56, s13
	v_perm_b32 v40, v57, v60, s13
	global_store_dwordx4 v[46:47], v[40:43], off
	v_and_b32_e32 v57, 0xffff0000, v104
	v_lshlrev_b32_e32 v56, 16, v104
	v_add_co_u32_e32 v40, vcc, s18, v38
	v_lshlrev_b32_e32 v60, 16, v105
	v_and_b32_e32 v1, 0xffff0000, v106
	v_lshlrev_b32_e32 v0, 16, v106
	v_lshl_add_u64 v[46:47], s[94:95], 0, v[16:17]
	v_addc_co_u32_e32 v41, vcc, 0, v39, vcc
	v_lshlrev_b32_e32 v62, 16, v107
	v_pk_fma_f32 v[50:51], v[50:51], v[54:55], v[0:1] op_sel_hi:[1,0,1]
	v_pk_fma_f32 v[44:45], v[44:45], v[54:55], v[62:63] op_sel_hi:[1,0,1]
	v_pk_fma_f32 v[58:59], v[58:59], v[54:55], v[60:61] op_sel_hi:[1,0,1]
	v_pk_fma_f32 v[48:49], v[48:49], v[54:55], v[56:57] op_sel_hi:[1,0,1]
	v_bfe_u32 v41, v44, 16, 1
	v_bfe_u32 v42, v51, 16, 1
	v_bfe_u32 v43, v50, 16, 1
	v_bfe_u32 v55, v59, 16, 1
	v_bfe_u32 v56, v58, 16, 1
	v_bfe_u32 v57, v49, 16, 1
	v_bfe_u32 v60, v48, 16, 1
	v_add3_u32 v60, v48, v60, s12
	v_add3_u32 v57, v49, v57, s12
	v_add3_u32 v56, v58, v56, s12
	v_add3_u32 v55, v59, v55, s12
	v_add3_u32 v61, v50, v43, s12
	v_add3_u32 v42, v51, v42, s12
	v_add3_u32 v41, v44, v41, s12
	v_perm_b32 v42, v42, v61, s13
	v_lshl_add_u64 v[16:17], v[16:17], 0, s[6:7]
	s_waitcnt vmcnt(21)
	v_and_b32_e32 v61, 0xffff0000, v109
	v_and_b32_e32 v63, 0xffff0000, v111
	s_waitcnt vmcnt(20)
	v_mul_f32_e32 v40, 0x3fb8aa3b, v142
	v_exp_f32_e32 v54, v40
	v_bfe_u32 v40, v45, 16, 1
	v_add3_u32 v40, v45, v40, s12
	v_perm_b32 v43, v40, v41, s13
	v_perm_b32 v41, v55, v56, s13
	v_perm_b32 v40, v57, v60, s13
	global_store_dwordx4 v[46:47], v[40:43], off
	v_and_b32_e32 v57, 0xffff0000, v108
	v_lshlrev_b32_e32 v56, 16, v108
	v_add_co_u32_e32 v40, vcc, s19, v38
	v_lshlrev_b32_e32 v60, 16, v109
	v_and_b32_e32 v1, 0xffff0000, v110
	v_lshlrev_b32_e32 v0, 16, v110
	v_lshl_add_u64 v[46:47], s[94:95], 0, v[14:15]
	v_addc_co_u32_e32 v41, vcc, 0, v39, vcc
	v_lshlrev_b32_e32 v62, 16, v111
	v_pk_fma_f32 v[50:51], v[50:51], v[54:55], v[0:1] op_sel_hi:[1,0,1]
	v_pk_fma_f32 v[44:45], v[44:45], v[54:55], v[62:63] op_sel_hi:[1,0,1]
	v_pk_fma_f32 v[58:59], v[58:59], v[54:55], v[60:61] op_sel_hi:[1,0,1]
	v_pk_fma_f32 v[48:49], v[48:49], v[54:55], v[56:57] op_sel_hi:[1,0,1]
	v_bfe_u32 v41, v44, 16, 1
	v_bfe_u32 v42, v51, 16, 1
	v_bfe_u32 v43, v50, 16, 1
	v_bfe_u32 v55, v59, 16, 1
	v_bfe_u32 v56, v58, 16, 1
	v_bfe_u32 v57, v49, 16, 1
	v_bfe_u32 v60, v48, 16, 1
	v_add3_u32 v60, v48, v60, s12
	v_add3_u32 v57, v49, v57, s12
	v_add3_u32 v56, v58, v56, s12
	v_add3_u32 v55, v59, v55, s12
	v_add3_u32 v61, v50, v43, s12
	v_add3_u32 v42, v51, v42, s12
	v_add3_u32 v41, v44, v41, s12
	v_perm_b32 v42, v42, v61, s13
	v_lshl_add_u64 v[14:15], v[14:15], 0, s[6:7]
	s_waitcnt vmcnt(20)
	v_and_b32_e32 v61, 0xffff0000, v113
	v_and_b32_e32 v63, 0xffff0000, v115
	s_waitcnt vmcnt(19)
	v_mul_f32_e32 v40, 0x3fb8aa3b, v143
	v_exp_f32_e32 v54, v40
	v_bfe_u32 v40, v45, 16, 1
	v_add3_u32 v40, v45, v40, s12
	v_perm_b32 v43, v40, v41, s13
	v_perm_b32 v41, v55, v56, s13
	v_perm_b32 v40, v57, v60, s13
	global_store_dwordx4 v[46:47], v[40:43], off
	v_and_b32_e32 v57, 0xffff0000, v112
	v_lshlrev_b32_e32 v56, 16, v112
	v_add_co_u32_e32 v40, vcc, s20, v38
	v_lshlrev_b32_e32 v60, 16, v113
	v_and_b32_e32 v1, 0xffff0000, v114
	v_lshlrev_b32_e32 v0, 16, v114
	v_lshl_add_u64 v[46:47], s[94:95], 0, v[12:13]
	v_addc_co_u32_e32 v41, vcc, 0, v39, vcc
	v_lshlrev_b32_e32 v62, 16, v115
	v_pk_fma_f32 v[50:51], v[50:51], v[54:55], v[0:1] op_sel_hi:[1,0,1]
	v_pk_fma_f32 v[44:45], v[44:45], v[54:55], v[62:63] op_sel_hi:[1,0,1]
	v_pk_fma_f32 v[58:59], v[58:59], v[54:55], v[60:61] op_sel_hi:[1,0,1]
	v_pk_fma_f32 v[48:49], v[48:49], v[54:55], v[56:57] op_sel_hi:[1,0,1]
	v_bfe_u32 v41, v44, 16, 1
	v_bfe_u32 v42, v51, 16, 1
	v_bfe_u32 v43, v50, 16, 1
	v_bfe_u32 v55, v59, 16, 1
	v_bfe_u32 v56, v58, 16, 1
	v_bfe_u32 v57, v49, 16, 1
	v_bfe_u32 v60, v48, 16, 1
	v_add3_u32 v60, v48, v60, s12
	v_add3_u32 v57, v49, v57, s12
	v_add3_u32 v56, v58, v56, s12
	v_add3_u32 v55, v59, v55, s12
	v_add3_u32 v61, v50, v43, s12
	v_add3_u32 v42, v51, v42, s12
	v_add3_u32 v41, v44, v41, s12
	v_perm_b32 v42, v42, v61, s13
	v_lshl_add_u64 v[12:13], v[12:13], 0, s[6:7]
	s_waitcnt vmcnt(19)
	v_and_b32_e32 v61, 0xffff0000, v117
	v_and_b32_e32 v63, 0xffff0000, v119
	s_waitcnt vmcnt(18)
; DEVINL u16 f2bf(float f) { uint32_t u = __float_as_uint(f); u += 0x7FFFu + ((u >> 16) & 1u); return (u16)(u >> 16); }
; DEVINL float bfs2f(short h) { return __uint_as_float(((uint32_t)(u16)h) << 16); }
; DEVINL int opaque_tid(int wv) { int t = (wv << 6) | (int)__builtin_amdgcn_mbcnt_hi(~0u, __builtin_amdgcn_mbcnt_lo(~0u, 0u)); asm volatile("" : "+v"(t)); return t; }
; DEVINL void phase_scan(const Params& p, int layer, int wv) {
;     ...
;   for (int idx = blockIdx.x * NTHR + opaque_tid(wv); idx < total; idx += gridDim.x * NTHR) {
;     const int bh = idx >> 10, e = (idx & 1023) * 8;
;     const int b = bh >> 4, hd = bh & 15;
;     float carry[8];
; #pragma unroll
;     for (int k = 0; k < 8; ++k) carry[k] = 0.f;
; #pragma unroll 16
;     for (int c = 0; c < 32; ++c) {
;       u16* sp = stg + ((size_t)((b * 32 + c) * 16 + hd)) * 8192 + e;
;       bf16x8 r = *(const bf16x8*)sp;
;       float cd = __expf(acumg[(size_t)(b * SEQ + c * 128 + 127) * 16 + hd]);
;       bf16x8 o;
; #pragma unroll
;       for (int k = 0; k < 8; ++k) { o[k] = (short)f2bf(carry[k]); carry[k] = carry[k] * cd + bfs2f(r[k]); }
;       *(bf16x8*)sp = o;
;     }
	v_mul_f32_e32 v40, 0x3fb8aa3b, v144
	v_exp_f32_e32 v54, v40
	v_bfe_u32 v40, v45, 16, 1
	v_add3_u32 v40, v45, v40, s12
	v_perm_b32 v43, v40, v41, s13
	v_perm_b32 v41, v55, v56, s13
	v_perm_b32 v40, v57, v60, s13
	global_store_dwordx4 v[46:47], v[40:43], off
	v_and_b32_e32 v57, 0xffff0000, v116
	v_lshlrev_b32_e32 v56, 16, v116
	v_add_co_u32_e32 v40, vcc, s21, v38
	v_lshlrev_b32_e32 v60, 16, v117
	v_and_b32_e32 v1, 0xffff0000, v118
	v_lshlrev_b32_e32 v0, 16, v118
	v_lshl_add_u64 v[46:47], s[94:95], 0, v[10:11]
	v_addc_co_u32_e32 v41, vcc, 0, v39, vcc
	v_lshlrev_b32_e32 v62, 16, v119
	v_pk_fma_f32 v[50:51], v[50:51], v[54:55], v[0:1] op_sel_hi:[1,0,1]
	v_pk_fma_f32 v[44:45], v[44:45], v[54:55], v[62:63] op_sel_hi:[1,0,1]
	v_pk_fma_f32 v[58:59], v[58:59], v[54:55], v[60:61] op_sel_hi:[1,0,1]
	v_pk_fma_f32 v[48:49], v[48:49], v[54:55], v[56:57] op_sel_hi:[1,0,1]
	v_bfe_u32 v41, v44, 16, 1
	v_bfe_u32 v42, v51, 16, 1
	v_bfe_u32 v43, v50, 16, 1
	v_bfe_u32 v55, v59, 16, 1
	v_bfe_u32 v56, v58, 16, 1
	v_bfe_u32 v57, v49, 16, 1
	v_bfe_u32 v60, v48, 16, 1
	v_add3_u32 v60, v48, v60, s12
	v_add3_u32 v57, v49, v57, s12
	v_add3_u32 v56, v58, v56, s12
	v_add3_u32 v55, v59, v55, s12
	v_add3_u32 v61, v50, v43, s12
	v_add3_u32 v42, v51, v42, s12
	v_add3_u32 v41, v44, v41, s12
	v_perm_b32 v42, v42, v61, s13
	v_lshl_add_u64 v[10:11], v[10:11], 0, s[6:7]
	s_waitcnt vmcnt(18)
	v_and_b32_e32 v61, 0xffff0000, v121
	v_and_b32_e32 v63, 0xffff0000, v123
	s_waitcnt vmcnt(17)
	v_mul_f32_e32 v40, 0x3fb8aa3b, v145
	v_exp_f32_e32 v54, v40
	v_bfe_u32 v40, v45, 16, 1
	v_add3_u32 v40, v45, v40, s12
	v_perm_b32 v43, v40, v41, s13
	v_perm_b32 v41, v55, v56, s13
	v_perm_b32 v40, v57, v60, s13
	v_and_b32_e32 v57, 0xffff0000, v120
	v_lshlrev_b32_e32 v56, 16, v120
	v_lshlrev_b32_e32 v60, 16, v121
	v_and_b32_e32 v1, 0xffff0000, v122
	v_lshlrev_b32_e32 v0, 16, v122
	v_lshlrev_b32_e32 v62, 16, v123
	global_store_dwordx4 v[46:47], v[40:43], off
	v_pk_fma_f32 v[44:45], v[44:45], v[54:55], v[62:63] op_sel_hi:[1,0,1]
	v_pk_fma_f32 v[62:63], v[50:51], v[54:55], v[0:1] op_sel_hi:[1,0,1]
	v_add_co_u32_e32 v40, vcc, s22, v38
	v_pk_fma_f32 v[58:59], v[58:59], v[54:55], v[60:61] op_sel_hi:[1,0,1]
	v_pk_fma_f32 v[54:55], v[48:49], v[54:55], v[56:57] op_sel_hi:[1,0,1]
	v_lshl_add_u64 v[56:57], s[94:95], 0, v[8:9]
	v_addc_co_u32_e32 v41, vcc, 0, v39, vcc
	v_bfe_u32 v42, v63, 16, 1
	v_bfe_u32 v41, v44, 16, 1
	v_bfe_u32 v43, v62, 16, 1
	v_bfe_u32 v47, v59, 16, 1
	v_bfe_u32 v48, v58, 16, 1
	v_bfe_u32 v49, v55, 16, 1
	v_bfe_u32 v50, v54, 16, 1
	v_add3_u32 v60, v54, v50, s12
	v_add3_u32 v61, v55, v49, s12
	v_add3_u32 v48, v58, v48, s12
	v_add3_u32 v47, v59, v47, s12
	v_add3_u32 v43, v62, v43, s12
	v_add3_u32 v42, v63, v42, s12
	v_add3_u32 v41, v44, v41, s12
	v_perm_b32 v50, v42, v43, s13
	v_perm_b32 v49, v47, v48, s13
	v_perm_b32 v48, v61, v60, s13
	v_add_co_u32_e32 v38, vcc, s23, v38
	v_lshl_add_u64 v[8:9], v[8:9], 0, s[6:7]
	s_nop 0
	v_addc_co_u32_e32 v39, vcc, 0, v39, vcc
	s_waitcnt vmcnt(17)
	v_and_b32_e32 v61, 0xffff0000, v124
	v_lshlrev_b32_e32 v60, 16, v124
	s_waitcnt vmcnt(16)
	v_mul_f32_e32 v40, 0x3fb8aa3b, v146
	v_exp_f32_e32 v46, v40
	v_bfe_u32 v40, v45, 16, 1
	v_add3_u32 v40, v45, v40, s12
	v_perm_b32 v51, v40, v41, s13
	v_and_b32_e32 v65, 0xffff0000, v125
	v_lshlrev_b32_e32 v64, 16, v125
	v_and_b32_e32 v1, 0xffff0000, v126
	v_lshlrev_b32_e32 v0, 16, v126
	global_store_dwordx4 v[56:57], v[48:51], off
	v_and_b32_e32 v41, 0xffff0000, v127
	v_lshlrev_b32_e32 v40, 16, v127
	v_lshl_add_u64 v[48:49], s[94:95], 0, v[4:5]
	v_pk_fma_f32 v[42:43], v[62:63], v[46:47], v[0:1] op_sel_hi:[1,0,1]
	v_pk_fma_f32 v[40:41], v[44:45], v[46:47], v[40:41] op_sel_hi:[1,0,1]
	v_pk_fma_f32 v[44:45], v[58:59], v[46:47], v[64:65] op_sel_hi:[1,0,1]
	v_pk_fma_f32 v[46:47], v[54:55], v[46:47], v[60:61] op_sel_hi:[1,0,1]
	v_bfe_u32 v39, v41, 16, 1
	v_bfe_u32 v50, v40, 16, 1
	v_bfe_u32 v51, v43, 16, 1
	v_bfe_u32 v54, v42, 16, 1
	v_bfe_u32 v55, v45, 16, 1
	v_bfe_u32 v56, v44, 16, 1
	v_bfe_u32 v57, v47, 16, 1
	v_bfe_u32 v58, v46, 16, 1
	v_add3_u32 v58, v46, v58, s12
	v_add3_u32 v59, v47, v57, s12
	v_add3_u32 v60, v44, v56, s12
	v_add3_u32 v55, v45, v55, s12
	v_add3_u32 v54, v42, v54, s12
	v_add3_u32 v51, v43, v51, s12
	v_add3_u32 v50, v40, v50, s12
	v_add3_u32 v39, v41, v39, s12
	v_perm_b32 v57, v39, v50, s13
	v_perm_b32 v56, v51, v54, s13
	v_perm_b32 v55, v55, v60, s13
	v_perm_b32 v54, v59, v58, s13
	v_lshl_add_u64 v[4:5], v[4:5], 0, s[6:7]
	global_store_dwordx4 v[48:49], v[54:57], off
	s_waitcnt vmcnt(16)
	v_and_b32_e32 v59, 0xffff0000, v128
	v_lshlrev_b32_e32 v58, 16, v128
	s_waitcnt vmcnt(15)
	v_mul_f32_e32 v38, 0x3fb8aa3b, v147
	v_exp_f32_e32 v38, v38
	v_and_b32_e32 v61, 0xffff0000, v129
	v_lshlrev_b32_e32 v60, 16, v129
	v_and_b32_e32 v1, 0xffff0000, v130
	v_lshlrev_b32_e32 v0, 16, v130
	v_and_b32_e32 v51, 0xffff0000, v131
	v_lshlrev_b32_e32 v50, 16, v131
	v_pk_fma_f32 v[50:51], v[40:41], v[38:39], v[50:51] op_sel_hi:[1,0,1]
	v_pk_fma_f32 v[40:41], v[42:43], v[38:39], v[0:1] op_sel_hi:[1,0,1]
	v_pk_fma_f32 v[2:3], v[44:45], v[38:39], v[60:61] op_sel_hi:[1,0,1]
	v_pk_fma_f32 v[0:1], v[46:47], v[38:39], v[58:59] op_sel_hi:[1,0,1]
	s_cbranch_scc0 .LBB0_757
	v_add_u32_e32 v52, s10, v52
	v_cmp_lt_i32_e32 vcc, s24, v52
	s_or_b64 s[2:3], vcc, s[2:3]
	v_add_u32_e32 v53, s11, v53
	s_andn2_b64 exec, exec, s[2:3]
	s_cbranch_execnz .LBB0_756
